# top-k: bitwise threshold search on ballot counts with early exit when a candidate selects exactly 16 keys (replaces LDS key broadcast + 64 cmp/addc rank)
# speedup vs baseline: 1.0095x; 1.0052x over previous
.LBB0_1145:
	s_or_b64 exec, exec, s[8:9]
	v_and_b32_e32 v34, 0xffffffc0, v37
	v_add_u32_e32 v34, v34, v40
	v_cndmask_b32_e64 v34, v34, v39, s[0:1]
	v_cndmask_b32_e64 v47, v34, v41, s[6:7]
	s_mov_b32 s14, 0
	s_or_b32 s15, s14, 0x80000000
	v_cmp_le_u32_e64 s[10:11], s15, v47
	s_bcnt1_i32_b64 s8, s[10:11]
	s_cmp_eq_u32 s8, 16
	s_cbranch_scc1 .Ltk_done
	s_cmp_gt_u32 s8, 15
	s_cselect_b32 s14, s15, s14
	s_or_b32 s15, s14, 0x40000000
	v_cmp_le_u32_e64 s[10:11], s15, v47
	s_bcnt1_i32_b64 s8, s[10:11]
	s_cmp_eq_u32 s8, 16
	s_cbranch_scc1 .Ltk_done
	s_cmp_gt_u32 s8, 15
	s_cselect_b32 s14, s15, s14
	s_or_b32 s15, s14, 0x20000000
	v_cmp_le_u32_e64 s[10:11], s15, v47
	s_bcnt1_i32_b64 s8, s[10:11]
	s_cmp_eq_u32 s8, 16
	s_cbranch_scc1 .Ltk_done
	s_cmp_gt_u32 s8, 15
	s_cselect_b32 s14, s15, s14
	s_or_b32 s15, s14, 0x10000000
	v_cmp_le_u32_e64 s[10:11], s15, v47
	s_bcnt1_i32_b64 s8, s[10:11]
	s_cmp_eq_u32 s8, 16
	s_cbranch_scc1 .Ltk_done
	s_cmp_gt_u32 s8, 15
	s_cselect_b32 s14, s15, s14
	s_or_b32 s15, s14, 0x8000000
	v_cmp_le_u32_e64 s[10:11], s15, v47
	s_bcnt1_i32_b64 s8, s[10:11]
	s_cmp_eq_u32 s8, 16
	s_cbranch_scc1 .Ltk_done
	s_cmp_gt_u32 s8, 15
	s_cselect_b32 s14, s15, s14
	s_or_b32 s15, s14, 0x4000000
	v_cmp_le_u32_e64 s[10:11], s15, v47
	s_bcnt1_i32_b64 s8, s[10:11]
	s_cmp_eq_u32 s8, 16
	s_cbranch_scc1 .Ltk_done
	s_cmp_gt_u32 s8, 15
	s_cselect_b32 s14, s15, s14
	s_or_b32 s15, s14, 0x2000000
	v_cmp_le_u32_e64 s[10:11], s15, v47
	s_bcnt1_i32_b64 s8, s[10:11]
	s_cmp_eq_u32 s8, 16
	s_cbranch_scc1 .Ltk_done
	s_cmp_gt_u32 s8, 15
	s_cselect_b32 s14, s15, s14
	s_or_b32 s15, s14, 0x1000000
	v_cmp_le_u32_e64 s[10:11], s15, v47
	s_bcnt1_i32_b64 s8, s[10:11]
	s_cmp_eq_u32 s8, 16
	s_cbranch_scc1 .Ltk_done
	s_cmp_gt_u32 s8, 15
	s_cselect_b32 s14, s15, s14
	s_or_b32 s15, s14, 0x800000
	v_cmp_le_u32_e64 s[10:11], s15, v47
	s_bcnt1_i32_b64 s8, s[10:11]
	s_cmp_eq_u32 s8, 16
	s_cbranch_scc1 .Ltk_done
	s_cmp_gt_u32 s8, 15
	s_cselect_b32 s14, s15, s14
	s_or_b32 s15, s14, 0x400000
	v_cmp_le_u32_e64 s[10:11], s15, v47
	s_bcnt1_i32_b64 s8, s[10:11]
	s_cmp_eq_u32 s8, 16
	s_cbranch_scc1 .Ltk_done
	s_cmp_gt_u32 s8, 15
	s_cselect_b32 s14, s15, s14
	s_or_b32 s15, s14, 0x200000
	v_cmp_le_u32_e64 s[10:11], s15, v47
	s_bcnt1_i32_b64 s8, s[10:11]
	s_cmp_eq_u32 s8, 16
	s_cbranch_scc1 .Ltk_done
	s_cmp_gt_u32 s8, 15
	s_cselect_b32 s14, s15, s14
	s_or_b32 s15, s14, 0x100000
	v_cmp_le_u32_e64 s[10:11], s15, v47
	s_bcnt1_i32_b64 s8, s[10:11]
	s_cmp_eq_u32 s8, 16
	s_cbranch_scc1 .Ltk_done
	s_cmp_gt_u32 s8, 15
	s_cselect_b32 s14, s15, s14
	s_or_b32 s15, s14, 0x80000
	v_cmp_le_u32_e64 s[10:11], s15, v47
	s_bcnt1_i32_b64 s8, s[10:11]
	s_cmp_eq_u32 s8, 16
	s_cbranch_scc1 .Ltk_done
	s_cmp_gt_u32 s8, 15
	s_cselect_b32 s14, s15, s14
	s_or_b32 s15, s14, 0x40000
	v_cmp_le_u32_e64 s[10:11], s15, v47
	s_bcnt1_i32_b64 s8, s[10:11]
	s_cmp_eq_u32 s8, 16
	s_cbranch_scc1 .Ltk_done
	s_cmp_gt_u32 s8, 15
	s_cselect_b32 s14, s15, s14
	s_or_b32 s15, s14, 0x20000
	v_cmp_le_u32_e64 s[10:11], s15, v47
	s_bcnt1_i32_b64 s8, s[10:11]
	s_cmp_eq_u32 s8, 16
	s_cbranch_scc1 .Ltk_done
	s_cmp_gt_u32 s8, 15
	s_cselect_b32 s14, s15, s14
	s_or_b32 s15, s14, 0x10000
	v_cmp_le_u32_e64 s[10:11], s15, v47
	s_bcnt1_i32_b64 s8, s[10:11]
	s_cmp_eq_u32 s8, 16
	s_cbranch_scc1 .Ltk_done
	s_cmp_gt_u32 s8, 15
	s_cselect_b32 s14, s15, s14
	s_or_b32 s15, s14, 0x8000
	v_cmp_le_u32_e64 s[10:11], s15, v47
	s_bcnt1_i32_b64 s8, s[10:11]
	s_cmp_eq_u32 s8, 16
	s_cbranch_scc1 .Ltk_done
	s_cmp_gt_u32 s8, 15
	s_cselect_b32 s14, s15, s14
	s_or_b32 s15, s14, 0x4000
	v_cmp_le_u32_e64 s[10:11], s15, v47
	s_bcnt1_i32_b64 s8, s[10:11]
	s_cmp_eq_u32 s8, 16
	s_cbranch_scc1 .Ltk_done
	s_cmp_gt_u32 s8, 15
	s_cselect_b32 s14, s15, s14
	s_or_b32 s15, s14, 0x2000
	v_cmp_le_u32_e64 s[10:11], s15, v47
	s_bcnt1_i32_b64 s8, s[10:11]
	s_cmp_eq_u32 s8, 16
	s_cbranch_scc1 .Ltk_done
	s_cmp_gt_u32 s8, 15
	s_cselect_b32 s14, s15, s14
	s_or_b32 s15, s14, 0x1000
	v_cmp_le_u32_e64 s[10:11], s15, v47
	s_bcnt1_i32_b64 s8, s[10:11]
	s_cmp_eq_u32 s8, 16
	s_cbranch_scc1 .Ltk_done
	s_cmp_gt_u32 s8, 15
	s_cselect_b32 s14, s15, s14
	s_or_b32 s15, s14, 0x800
	v_cmp_le_u32_e64 s[10:11], s15, v47
	s_bcnt1_i32_b64 s8, s[10:11]
	s_cmp_eq_u32 s8, 16
	s_cbranch_scc1 .Ltk_done
	s_cmp_gt_u32 s8, 15
	s_cselect_b32 s14, s15, s14
	s_or_b32 s15, s14, 0x400
	v_cmp_le_u32_e64 s[10:11], s15, v47
	s_bcnt1_i32_b64 s8, s[10:11]
	s_cmp_eq_u32 s8, 16
	s_cbranch_scc1 .Ltk_done
	s_cmp_gt_u32 s8, 15
	s_cselect_b32 s14, s15, s14
	s_or_b32 s15, s14, 0x200
	v_cmp_le_u32_e64 s[10:11], s15, v47
	s_bcnt1_i32_b64 s8, s[10:11]
	s_cmp_eq_u32 s8, 16
	s_cbranch_scc1 .Ltk_done
	s_cmp_gt_u32 s8, 15
	s_cselect_b32 s14, s15, s14
	s_or_b32 s15, s14, 0x100
	v_cmp_le_u32_e64 s[10:11], s15, v47
	s_bcnt1_i32_b64 s8, s[10:11]
	s_cmp_eq_u32 s8, 16
	s_cbranch_scc1 .Ltk_done
	s_cmp_gt_u32 s8, 15
	s_cselect_b32 s14, s15, s14
	s_or_b32 s15, s14, 0x80
	v_cmp_le_u32_e64 s[10:11], s15, v47
	s_bcnt1_i32_b64 s8, s[10:11]
	s_cmp_eq_u32 s8, 16
	s_cbranch_scc1 .Ltk_done
	s_cmp_gt_u32 s8, 15
	s_cselect_b32 s14, s15, s14
	s_or_b32 s15, s14, 64
	v_cmp_le_u32_e64 s[10:11], s15, v47
	s_bcnt1_i32_b64 s8, s[10:11]
	s_cmp_eq_u32 s8, 16
	s_cbranch_scc1 .Ltk_done
	s_cmp_gt_u32 s8, 15
	s_cselect_b32 s14, s15, s14
	s_or_b32 s15, s14, 32
	v_cmp_le_u32_e64 s[10:11], s15, v47
	s_bcnt1_i32_b64 s8, s[10:11]
	s_cmp_eq_u32 s8, 16
	s_cbranch_scc1 .Ltk_done
	s_cmp_gt_u32 s8, 15
	s_cselect_b32 s14, s15, s14
	s_or_b32 s15, s14, 16
	v_cmp_le_u32_e64 s[10:11], s15, v47
	s_bcnt1_i32_b64 s8, s[10:11]
	s_cmp_eq_u32 s8, 16
	s_cbranch_scc1 .Ltk_done
	s_cmp_gt_u32 s8, 15
	s_cselect_b32 s14, s15, s14
	s_or_b32 s15, s14, 8
	v_cmp_le_u32_e64 s[10:11], s15, v47
	s_bcnt1_i32_b64 s8, s[10:11]
	s_cmp_eq_u32 s8, 16
	s_cbranch_scc1 .Ltk_done
	s_cmp_gt_u32 s8, 15
	s_cselect_b32 s14, s15, s14
	s_or_b32 s15, s14, 4
	v_cmp_le_u32_e64 s[10:11], s15, v47
	s_bcnt1_i32_b64 s8, s[10:11]
	s_cmp_eq_u32 s8, 16
	s_cbranch_scc1 .Ltk_done
	s_cmp_gt_u32 s8, 15
	s_cselect_b32 s14, s15, s14
	s_or_b32 s15, s14, 2
	v_cmp_le_u32_e64 s[10:11], s15, v47
	s_bcnt1_i32_b64 s8, s[10:11]
	s_cmp_eq_u32 s8, 16
	s_cbranch_scc1 .Ltk_done
	s_cmp_gt_u32 s8, 15
	s_cselect_b32 s14, s15, s14
	s_or_b32 s15, s14, 1
	v_cmp_le_u32_e64 s[10:11], s15, v47
	s_bcnt1_i32_b64 s8, s[10:11]
	s_cmp_eq_u32 s8, 16
	s_cbranch_scc1 .Ltk_done
	s_cmp_gt_u32 s8, 15
	s_cselect_b32 s14, s15, s14
	v_cmp_le_u32_e64 s[10:11], s14, v47
.Ltk_done:
	s_and_saveexec_b64 s[8:9], s[4:5]
	s_cbranch_execz .LBB0_1140
	v_add_u32_e32 v34, 0, v46
	v_mov_b64_e32 v[36:37], s[10:11]
	ds_write_b64 v34, v[36:37]
	s_branch .LBB0_1140
